# HGRN c2 scan: 8 steps per trip with 16 loads in flight (two copies of the 4-step body on disjoint registers)
# baseline (speedup 1.0000x reference)
; DEV int tidx() { int t = threadIdx.x; asm volatile("" : "+v"(t)); return t; }
; DEV unsigned pack2(float a, float b) { f32x2 v = {a, b}; return __builtin_bit_cast(unsigned, __builtin_convertvector(v, bf2_t)); }
; DEV float bflo(unsigned u) { return __uint_as_float(u << 16); }
; DEV float bfhi(unsigned u) { return __uint_as_float(u & 0xffff0000u); }
; DEV void phase_hg_c2(const Params& p) {
;   bf16_t* DS = WSP(bf16_t, L1_DS); const float* DEC = WSP(float, S_DECAY);
;   for (int idx = blockIdx.x * 256 + tidx(); idx < 32 * 128 * 32; idx += gridDim.x * 256) {
;     const int k4 = idx & 31, dv = (idx >> 5) & 127, chain = idx >> 12;
;     bf16_t* dp = DS + (size_t)chain * 132 * 16384 + dv * 128 + k4 * 4;
;     const float* dc = DEC + (size_t)chain * 132 * 128 + k4 * 4;
;     float s0 = 0.f, s1 = 0.f, s2 = 0.f, s3 = 0.f;
;     for (int st = 0; st < 132; st += 4) {
;       uint2 d[4]; float4 dd[4];
; #pragma unroll
;       for (int u = 0; u < 4; u++) { d[u] = *(const uint2*)(dp + (size_t)(st + u) * 16384); dd[u] = *(const float4*)(dc + (size_t)(st + u) * 128); }
; #pragma unroll
;       for (int u = 0; u < 4; u++) {
;         uint2 o; o.x = pack2(s0, s1); o.y = pack2(s2, s3);
;         *(uint2*)(dp + (size_t)(st + u) * 16384) = o;
;         s0 = dd[u].x * s0 + bflo(d[u].x); s1 = dd[u].y * s1 + bfhi(d[u].x);
;         s2 = dd[u].z * s2 + bflo(d[u].y); s3 = dd[u].w * s3 + bfhi(d[u].y);
;       }
;     }
;   }
.Lc2_dbl:
	s_waitcnt vmcnt(21)
	v_lshl_add_u64 v[24:25], s[28:29], 0, v[2:3]
	v_add_co_u32_e32 v28, vcc, 0x16800000, v24
	v_lshl_add_u64 v[12:13], s[28:29], 0, v[4:5]
	s_nop 0
	v_addc_co_u32_e32 v29, vcc, 0, v25, vcc
	v_add_co_u32_e32 v26, vcc, 0xc080000, v12
	global_load_dwordx2 v[30:31], v[28:29], off
	s_nop 0
	v_addc_co_u32_e32 v27, vcc, 0, v13, vcc
	s_waitcnt vmcnt(21)
	v_add_co_u32_e32 v32, vcc, 0x16808000, v24
	global_load_dwordx4 v[12:15], v[26:27], off
	s_nop 0
	v_addc_co_u32_e32 v33, vcc, 0, v25, vcc
	v_add_co_u32_e32 v34, vcc, 0x16810000, v24
	global_load_dwordx4 v[16:19], v[26:27], off offset:512
	global_load_dwordx4 v[20:23], v[26:27], off offset:1024
	global_load_dwordx2 v[36:37], v[32:33], off
	v_addc_co_u32_e32 v35, vcc, 0, v25, vcc
	s_waitcnt vmcnt(24)
	v_add_co_u32_e32 v38, vcc, 0x16818000, v24
	global_load_dwordx2 v[40:41], v[34:35], off
	s_nop 0
	v_addc_co_u32_e32 v39, vcc, 0, v25, vcc
	global_load_dwordx2 v[42:43], v[38:39], off
	s_nop 0
	global_load_dwordx4 v[24:27], v[26:27], off offset:1536
	s_mov_b64 s[8:9], 0x20000
	v_lshl_add_u64 v[2:3], v[2:3], 0, s[8:9]
	s_mov_b64 s[8:9], 0x800
	v_lshl_add_u64 v[4:5], v[4:5], 0, s[8:9]
	v_lshl_add_u64 v[72:73], s[28:29], 0, v[2:3]
	v_add_co_u32_e32 v76, vcc, 0x16800000, v72
	v_lshl_add_u64 v[60:61], s[28:29], 0, v[4:5]
	s_nop 0
	v_addc_co_u32_e32 v77, vcc, 0, v73, vcc
	v_add_co_u32_e32 v74, vcc, 0xc080000, v60
	global_load_dwordx2 v[78:79], v[76:77], off
	s_nop 0
	v_addc_co_u32_e32 v75, vcc, 0, v61, vcc
	v_add_co_u32_e32 v80, vcc, 0x16808000, v72
	global_load_dwordx4 v[60:63], v[74:75], off
	s_nop 0
	v_addc_co_u32_e32 v81, vcc, 0, v73, vcc
	v_add_co_u32_e32 v82, vcc, 0x16810000, v72
	global_load_dwordx4 v[64:67], v[74:75], off offset:512
	global_load_dwordx4 v[68:71], v[74:75], off offset:1024
	global_load_dwordx2 v[84:85], v[80:81], off
	v_addc_co_u32_e32 v83, vcc, 0, v73, vcc
	v_add_co_u32_e32 v86, vcc, 0x16818000, v72
	global_load_dwordx2 v[88:89], v[82:83], off
	s_nop 0
	v_addc_co_u32_e32 v87, vcc, 0, v73, vcc
	global_load_dwordx2 v[90:91], v[86:87], off
	s_nop 0
	global_load_dwordx4 v[72:75], v[74:75], off offset:1536
	s_mov_b64 s[8:9], 0x20000
	v_lshl_add_u64 v[2:3], v[2:3], 0, s[8:9]
	s_mov_b64 s[8:9], 0x800
	v_lshl_add_u64 v[4:5], v[4:5], 0, s[8:9]
	v_cvt_pk_bf16_f32 v44, v10, v9
	v_cvt_pk_bf16_f32 v45, v8, v7
	global_store_dwordx2 v[28:29], v[44:45], off
	s_waitcnt vmcnt(16)
	v_lshlrev_b32_e32 v11, 16, v30
	v_and_b32_e32 v28, 0xffff0000, v30
	v_lshlrev_b32_e32 v29, 16, v31
	v_and_b32_e32 v30, 0xffff0000, v31
	s_waitcnt vmcnt(15)
	v_fmac_f32_e32 v11, v10, v12
	v_fmac_f32_e32 v28, v9, v13
	v_fmac_f32_e32 v29, v8, v14
	v_fmac_f32_e32 v30, v7, v15
	v_cvt_pk_bf16_f32 v8, v11, v28
	s_waitcnt vmcnt(12)
	v_lshlrev_b32_e32 v7, 16, v36
	v_and_b32_e32 v10, 0xffff0000, v36
	v_lshlrev_b32_e32 v14, 16, v37
	v_and_b32_e32 v15, 0xffff0000, v37
	v_cvt_pk_bf16_f32 v9, v29, v30
	v_fmac_f32_e32 v7, v11, v16
	v_fmac_f32_e32 v10, v28, v17
	v_fmac_f32_e32 v14, v29, v18
	v_fmac_f32_e32 v15, v30, v19
	s_waitcnt vmcnt(11)
	v_lshlrev_b32_e32 v11, 16, v40
	v_and_b32_e32 v16, 0xffff0000, v40
	v_lshlrev_b32_e32 v17, 16, v41
	v_and_b32_e32 v18, 0xffff0000, v41
	global_store_dwordx2 v[32:33], v[8:9], off
	v_cvt_pk_bf16_f32 v12, v7, v10
	v_cvt_pk_bf16_f32 v13, v14, v15
	v_fmac_f32_e32 v11, v7, v20
	v_fmac_f32_e32 v16, v10, v21
	v_fmac_f32_e32 v17, v14, v22
	v_fmac_f32_e32 v18, v15, v23
	s_waitcnt vmcnt(11)
	v_lshlrev_b32_e32 v10, 16, v42
	v_and_b32_e32 v9, 0xffff0000, v42
	v_lshlrev_b32_e32 v8, 16, v43
	v_and_b32_e32 v7, 0xffff0000, v43
	global_store_dwordx2 v[34:35], v[12:13], off
	v_cvt_pk_bf16_f32 v12, v11, v16
	v_cvt_pk_bf16_f32 v13, v17, v18
	s_waitcnt vmcnt(11)
	v_fmac_f32_e32 v10, v11, v24
	v_fmac_f32_e32 v9, v16, v25
	v_fmac_f32_e32 v8, v17, v26
	v_fmac_f32_e32 v7, v18, v27
	global_store_dwordx2 v[38:39], v[12:13], off
	v_cvt_pk_bf16_f32 v92, v10, v9
	v_cvt_pk_bf16_f32 v93, v8, v7
	global_store_dwordx2 v[76:77], v[92:93], off
	s_waitcnt vmcnt(12)
	v_lshlrev_b32_e32 v59, 16, v78
	v_and_b32_e32 v76, 0xffff0000, v78
	v_lshlrev_b32_e32 v77, 16, v79
	v_and_b32_e32 v78, 0xffff0000, v79
	s_waitcnt vmcnt(11)
	v_fmac_f32_e32 v59, v10, v60
	v_fmac_f32_e32 v76, v9, v61
	v_fmac_f32_e32 v77, v8, v62
	v_fmac_f32_e32 v78, v7, v63
	v_cvt_pk_bf16_f32 v8, v59, v76
	s_waitcnt vmcnt(8)
	v_lshlrev_b32_e32 v7, 16, v84
	v_and_b32_e32 v10, 0xffff0000, v84
	v_lshlrev_b32_e32 v62, 16, v85
	v_and_b32_e32 v63, 0xffff0000, v85
	v_cvt_pk_bf16_f32 v9, v77, v78
	v_fmac_f32_e32 v7, v59, v64
	v_fmac_f32_e32 v10, v76, v65
	v_fmac_f32_e32 v62, v77, v66
	v_fmac_f32_e32 v63, v78, v67
	s_waitcnt vmcnt(7)
	v_lshlrev_b32_e32 v59, 16, v88
	v_and_b32_e32 v64, 0xffff0000, v88
	v_lshlrev_b32_e32 v65, 16, v89
	v_and_b32_e32 v66, 0xffff0000, v89
	global_store_dwordx2 v[80:81], v[8:9], off
	v_cvt_pk_bf16_f32 v60, v7, v10
	v_cvt_pk_bf16_f32 v61, v62, v63
	v_fmac_f32_e32 v59, v7, v68
	v_fmac_f32_e32 v64, v10, v69
	v_fmac_f32_e32 v65, v62, v70
	v_fmac_f32_e32 v66, v63, v71
	s_waitcnt vmcnt(7)
	v_lshlrev_b32_e32 v10, 16, v90
	v_and_b32_e32 v9, 0xffff0000, v90
	v_lshlrev_b32_e32 v8, 16, v91
	v_and_b32_e32 v7, 0xffff0000, v91
	global_store_dwordx2 v[82:83], v[60:61], off
	v_cvt_pk_bf16_f32 v60, v59, v64
	v_cvt_pk_bf16_f32 v61, v65, v66
	s_waitcnt vmcnt(7)
	v_fmac_f32_e32 v10, v59, v72
	v_fmac_f32_e32 v9, v64, v73
	v_fmac_f32_e32 v8, v65, v74
	v_fmac_f32_e32 v7, v66, v75
	global_store_dwordx2 v[86:87], v[60:61], off
	s_add_i32 s6, s6, 8
	s_cmpk_lt_u32 s6, 0x7c
	s_cbranch_scc1 .Lc2_dbl
